# gated short-conv unit: all loads of both items issued together, tap weights hoisted out of the loop (prologue de-serialisation)
# speedup vs baseline: 1.0037x; 1.0023x over previous
; __device__ __forceinline__ void mixers_phase(const PP& p, int l, int hf, unsigned char* lds) {
;     ...
;     for (;;) {
;         __syncthreads();
;         if (tid == 0) *qslot = (int)atomicAdd(qcnt, 1u);
;         __syncthreads();
;         const int unit = __builtin_amdgcn_readfirstlane(*qslot);
;         if (unit >= 512 + 256) break;
;         if (unit < 512) { attn_unit2(proj, Y + (size_t)2 * TH * 1024, relb, lds, unit); continue; }
;         {
;             const float* cw = p.in(I_CONVW) + (size_t)l * 3 * 1024;
;             const int i0 = (unit - 512) * 8192 + tid;
; #pragma unroll 2
;             for (int k = 0; k < 16; ++k) {
;                 const int i = i0 + k * 512;
;                 const int row = i >> 7, c8 = (i & 127) * 8, t = row & (SEQ - 1);
;                 const bf16* src = proj + paddr(row, c8);
;                 constexpr size_t SEGS = (size_t)8 * TH * 128;
;                 float cb[8], a[8], bq[8], acc[8];
;                 unpk8(*(const u32x4*)(src), cb);
;                 unpk8(*(const u32x4*)(src + SEGS), a); unpk8(*(const u32x4*)(src + 2 * SEGS), bq);
;                 const f32x4 w2a = *(const f32x4*)(cw + 2048 + c8), w2b = *(const f32x4*)(cw + 2048 + c8 + 4);
; #pragma unroll
;                 for (int j = 0; j < 8; ++j) acc[j] = (j < 4 ? w2a[j] : w2b[j - 4]) * a[j] * bq[j];
;                 if (t >= 1) {
;                     unpk8(*(const u32x4*)(src - 128 + SEGS), a); unpk8(*(const u32x4*)(src - 128 + 2 * SEGS), bq);
;                     const f32x4 w1a = *(const f32x4*)(cw + 1024 + c8), w1b = *(const f32x4*)(cw + 1024 + c8 + 4);
; #pragma unroll
;                     for (int j = 0; j < 8; ++j) acc[j] += (j < 4 ? w1a[j] : w1b[j - 4]) * a[j] * bq[j];
;                 }
;                 if (t >= 2) {
;                     unpk8(*(const u32x4*)(src - 256 + SEGS), a); unpk8(*(const u32x4*)(src - 256 + 2 * SEGS), bq);
;                     const f32x4 w0a = *(const f32x4*)(cw + c8), w0b = *(const f32x4*)(cw + c8 + 4);
; #pragma unroll
;                     for (int j = 0; j < 8; ++j) acc[j] += (j < 4 ? w0a[j] : w0b[j - 4]) * a[j] * bq[j];
;                 }
;                 u32x4 o; o.x = pk2(cb[0] * acc[0], cb[1] * acc[1]); o.y = pk2(cb[2] * acc[2], cb[3] * acc[3]); o.z = pk2(cb[4] * acc[4], cb[5] * acc[5]); o.w = pk2(cb[6] * acc[6], cb[7] * acc[7]);
;                 *(u32x4*)(Y + (size_t)row * 1024 + c8) = o;
.LBB0_266:
	s_or_b64 exec, exec, s[6:7]
	s_add_i32 s2, 0, 0x20600
	s_cmp_lg_u32 s2, -1
	s_cselect_b32 s2, s2, 0
	s_cselect_b32 s6, s51, 0
	v_mov_b32_e32 v0, s2
	v_mov_b32_e32 v1, s6
	s_waitcnt lgkmcnt(0)
	s_barrier
	flat_load_dword v0, v[0:1] sc0 sc1
	s_waitcnt vmcnt(0)
	s_mov_b64 s[6:7], -1
	s_waitcnt lgkmcnt(0)
	v_readfirstlane_b32 s23, v0
	s_cmpk_gt_i32 s23, 0x2ff
	s_cbranch_scc1 .LBB0_261
	s_cmpk_gt_i32 s23, 0x1ff
	s_cbranch_scc0 .LBB0_279
	s_add_i32 s2, 0, 0x20418
	s_cmp_lg_u32 s2, -1
	s_cselect_b32 s2, s2, 0
	s_cselect_b32 s6, s51, 0
	v_mov_b32_e32 v0, s2
	v_mov_b32_e32 v1, s6
	flat_load_dwordx2 v[0:1], v[0:1] sc0 sc1
	s_waitcnt vmcnt(0)
	v_mov_b32_e32 v149, v189
	v_lshl_add_u32 v22, s23, 13, v155
	s_waitcnt lgkmcnt(0)
	v_readfirstlane_b32 s6, v0
	v_readfirstlane_b32 s2, v1
	s_add_u32 s6, s6, s22
	s_addc_u32 s7, s2, s1
	v_lshl_add_u64 v[4:5], s[6:7], 0, v[148:149]
	s_mov_b64 s[6:7], 0x2000
	v_lshl_add_u64 v[6:7], v[4:5], 0, s[6:7]
	s_mov_b64 s[6:7], 0x1000
	v_lshl_add_u64 v[8:9], v[4:5], 0, s[6:7]
	s_movk_i32 s2, 0xe000
	global_load_dwordx4 v[106:109], v[6:7], off
	global_load_dwordx4 v[110:113], v[6:7], off offset:16
	global_load_dwordx4 v[114:117], v[8:9], off
	global_load_dwordx4 v[118:121], v[8:9], off offset:16
	global_load_dwordx4 v[122:125], v[4:5], off
	global_load_dwordx4 v[126:129], v[4:5], off offset:16
	s_mov_b64 s[8:9], 0x2000000
	s_mov_b64 s[16:17], 0x4000000
	s_mov_b64 s[18:19], 0x2000
	s_branch .LBB0_270
.LBB0_270:
	v_add_u32_e32 v23, s2, v22
	v_add_u32_e32 v0, 0xffc02000, v23
	v_ashrrev_i32_e32 v10, 7, v0
	v_ashrrev_i32_e32 v11, 31, v10
	v_lshlrev_b64 v[0:1], 8, v[10:11]
	v_lshl_add_u64 v[20:21], v[144:145], 0, v[0:1]
	v_lshl_add_u64 v[46:47], v[20:21], 0, s[8:9]
	v_lshl_add_u64 v[48:49], v[20:21], 0, s[16:17]
	global_load_dwordx4 v[50:53], v[20:21], off
	global_load_dwordx4 v[54:57], v[46:47], off
	global_load_dwordx4 v[58:61], v[48:49], off
	global_load_dwordx4 v[62:65], v[46:47], off offset:-256
	global_load_dwordx4 v[66:69], v[48:49], off offset:-256
	global_load_dwordx4 v[70:73], v[46:47], off offset:-512
	global_load_dwordx4 v[74:77], v[48:49], off offset:-512
	global_load_dwordx4 v[78:81], v[20:21], off offset:1024
	global_load_dwordx4 v[82:85], v[46:47], off offset:1024
	global_load_dwordx4 v[86:89], v[48:49], off offset:1024
	global_load_dwordx4 v[90:93], v[46:47], off offset:768
	global_load_dwordx4 v[94:97], v[48:49], off offset:768
	global_load_dwordx4 v[98:101], v[46:47], off offset:512
	global_load_dwordx4 v[102:105], v[48:49], off offset:512
	v_and_b32_e32 v38, 0x7ff, v10
	v_add_u32_e32 v39, 4, v10
	v_and_b32_e32 v39, 0x7ff, v39
	v_lshlrev_b64 v[10:11], 11, v[10:11]
	v_lshl_add_u64 v[130:131], v[146:147], 0, v[10:11]
	v_lshl_add_u64 v[132:133], v[130:131], 0, s[18:19]
	s_waitcnt vmcnt(7)
	v_lshlrev_b32_e32 v32, 16, v54
	v_and_b32_e32 v33, 0xffff0000, v54
	v_lshlrev_b32_e32 v34, 16, v58
	v_and_b32_e32 v35, 0xffff0000, v58
	v_pk_mul_f32 v[24:25], v[106:107], v[32:33]
	v_pk_mul_f32 v[24:25], v[24:25], v[34:35]
	v_lshlrev_b32_e32 v32, 16, v55
	v_and_b32_e32 v33, 0xffff0000, v55
	v_lshlrev_b32_e32 v34, 16, v59
	v_and_b32_e32 v35, 0xffff0000, v59
	v_pk_mul_f32 v[26:27], v[108:109], v[32:33]
	v_pk_mul_f32 v[26:27], v[26:27], v[34:35]
	v_lshlrev_b32_e32 v32, 16, v56
	v_and_b32_e32 v33, 0xffff0000, v56
	v_lshlrev_b32_e32 v34, 16, v60
	v_and_b32_e32 v35, 0xffff0000, v60
	v_pk_mul_f32 v[28:29], v[110:111], v[32:33]
	v_pk_mul_f32 v[28:29], v[28:29], v[34:35]
	v_lshlrev_b32_e32 v32, 16, v57
	v_and_b32_e32 v33, 0xffff0000, v57
	v_lshlrev_b32_e32 v34, 16, v61
	v_and_b32_e32 v35, 0xffff0000, v61
	v_pk_mul_f32 v[30:31], v[112:113], v[32:33]
	v_pk_mul_f32 v[30:31], v[30:31], v[34:35]
	v_cmp_ne_u32_e32 vcc, 0, v38
	s_and_saveexec_b64 s[6:7], vcc
	v_lshlrev_b32_e32 v32, 16, v62
	v_and_b32_e32 v33, 0xffff0000, v62
	v_lshlrev_b32_e32 v34, 16, v66
	v_and_b32_e32 v35, 0xffff0000, v66
	v_pk_mul_f32 v[36:37], v[114:115], v[32:33]
	v_pk_fma_f32 v[24:25], v[36:37], v[34:35], v[24:25]
	v_lshlrev_b32_e32 v32, 16, v63
	v_and_b32_e32 v33, 0xffff0000, v63
	v_lshlrev_b32_e32 v34, 16, v67
	v_and_b32_e32 v35, 0xffff0000, v67
	v_pk_mul_f32 v[36:37], v[116:117], v[32:33]
	v_pk_fma_f32 v[26:27], v[36:37], v[34:35], v[26:27]
	v_lshlrev_b32_e32 v32, 16, v64
	v_and_b32_e32 v33, 0xffff0000, v64
	v_lshlrev_b32_e32 v34, 16, v68
	v_and_b32_e32 v35, 0xffff0000, v68
	v_pk_mul_f32 v[36:37], v[118:119], v[32:33]
	v_pk_fma_f32 v[28:29], v[36:37], v[34:35], v[28:29]
	v_lshlrev_b32_e32 v32, 16, v65
	v_and_b32_e32 v33, 0xffff0000, v65
	v_lshlrev_b32_e32 v34, 16, v69
	v_and_b32_e32 v35, 0xffff0000, v69
	v_pk_mul_f32 v[36:37], v[120:121], v[32:33]
	v_pk_fma_f32 v[30:31], v[36:37], v[34:35], v[30:31]
	s_or_b64 exec, exec, s[6:7]
	v_cmp_lt_u32_e32 vcc, 1, v38
	s_and_saveexec_b64 s[6:7], vcc
	v_lshlrev_b32_e32 v32, 16, v70
	v_and_b32_e32 v33, 0xffff0000, v70
	v_lshlrev_b32_e32 v34, 16, v74
	v_and_b32_e32 v35, 0xffff0000, v74
	v_pk_mul_f32 v[36:37], v[122:123], v[32:33]
	v_pk_fma_f32 v[24:25], v[36:37], v[34:35], v[24:25]
	v_lshlrev_b32_e32 v32, 16, v71
	v_and_b32_e32 v33, 0xffff0000, v71
	v_lshlrev_b32_e32 v34, 16, v75
	v_and_b32_e32 v35, 0xffff0000, v75
	v_pk_mul_f32 v[36:37], v[124:125], v[32:33]
	v_pk_fma_f32 v[26:27], v[36:37], v[34:35], v[26:27]
	v_lshlrev_b32_e32 v32, 16, v72
	v_and_b32_e32 v33, 0xffff0000, v72
	v_lshlrev_b32_e32 v34, 16, v76
	v_and_b32_e32 v35, 0xffff0000, v76
	v_pk_mul_f32 v[36:37], v[126:127], v[32:33]
	v_pk_fma_f32 v[28:29], v[36:37], v[34:35], v[28:29]
	v_lshlrev_b32_e32 v32, 16, v73
	v_and_b32_e32 v33, 0xffff0000, v73
	v_lshlrev_b32_e32 v34, 16, v77
	v_and_b32_e32 v35, 0xffff0000, v77
	v_pk_mul_f32 v[36:37], v[128:129], v[32:33]
	v_pk_fma_f32 v[30:31], v[36:37], v[34:35], v[30:31]
	s_or_b64 exec, exec, s[6:7]
	v_lshlrev_b32_e32 v32, 16, v50
	v_and_b32_e32 v33, 0xffff0000, v50
	v_pk_mul_f32 v[36:37], v[24:25], v[32:33]
	v_cvt_pk_bf16_f32 v40, v36, v37
	v_lshlrev_b32_e32 v32, 16, v51
	v_and_b32_e32 v33, 0xffff0000, v51
	v_pk_mul_f32 v[36:37], v[26:27], v[32:33]
	v_cvt_pk_bf16_f32 v41, v36, v37
	v_lshlrev_b32_e32 v32, 16, v52
	v_and_b32_e32 v33, 0xffff0000, v52
	v_pk_mul_f32 v[36:37], v[28:29], v[32:33]
	v_cvt_pk_bf16_f32 v42, v36, v37
	v_lshlrev_b32_e32 v32, 16, v53
	v_and_b32_e32 v33, 0xffff0000, v53
	v_pk_mul_f32 v[36:37], v[30:31], v[32:33]
	v_cvt_pk_bf16_f32 v43, v36, v37
	global_store_dwordx4 v[130:131], v[40:43], off
	s_waitcnt vmcnt(1)
; __device__ __forceinline__ size_t paddr(int row, int col) { return ((size_t)(col >> 7) * 16384 + (size_t)row) * 128 + (col & 127); }
; __device__ __forceinline__ size_t paddr(int row, int col) { return ((size_t)(col >> 7) * TH + (size_t)row) * 128 + (col & 127); }
; __device__ __forceinline__ unsigned pk2(float lo, float hi) { unsigned r; asm("v_cvt_pk_bf16_f32 %0, %1, %2" : "=v"(r) : "v"(lo), "v"(hi)); return r; }
; __device__ __forceinline__ void mixers_phase(const PP& p, int l, int hf, unsigned char* lds) {
;     ...
;             for (int k = 0; k < 16; ++k) {
;                 const int i = i0 + k * 512;
;                 const int row = i >> 7, c8 = (i & 127) * 8, t = row & (SEQ - 1);
;                 const bf16* src = proj + paddr(row, c8);
;                 constexpr size_t SEGS = (size_t)8 * TH * 128;
;                 float cb[8], a[8], bq[8], acc[8];
;                 unpk8(*(const u32x4*)(src), cb);
;                 unpk8(*(const u32x4*)(src + SEGS), a); unpk8(*(const u32x4*)(src + 2 * SEGS), bq);
;                 const f32x4 w2a = *(const f32x4*)(cw + 2048 + c8), w2b = *(const f32x4*)(cw + 2048 + c8 + 4);
; #pragma unroll
;                 for (int j = 0; j < 8; ++j) acc[j] = (j < 4 ? w2a[j] : w2b[j - 4]) * a[j] * bq[j];
;                 if (t >= 1) {
;                     unpk8(*(const u32x4*)(src - 128 + SEGS), a); unpk8(*(const u32x4*)(src - 128 + 2 * SEGS), bq);
;                     const f32x4 w1a = *(const f32x4*)(cw + 1024 + c8), w1b = *(const f32x4*)(cw + 1024 + c8 + 4);
; #pragma unroll
;                     for (int j = 0; j < 8; ++j) acc[j] += (j < 4 ? w1a[j] : w1b[j - 4]) * a[j] * bq[j];
;                 }
;                 if (t >= 2) {
;                     unpk8(*(const u32x4*)(src - 256 + SEGS), a); unpk8(*(const u32x4*)(src - 256 + 2 * SEGS), bq);
;                     const f32x4 w0a = *(const f32x4*)(cw + c8), w0b = *(const f32x4*)(cw + c8 + 4);
; #pragma unroll
;                     for (int j = 0; j < 8; ++j) acc[j] += (j < 4 ? w0a[j] : w0b[j - 4]) * a[j] * bq[j];
;                 }
;                 u32x4 o; o.x = pk2(cb[0] * acc[0], cb[1] * acc[1]); o.y = pk2(cb[2] * acc[2], cb[3] * acc[3]); o.z = pk2(cb[4] * acc[4], cb[5] * acc[5]); o.w = pk2(cb[6] * acc[6], cb[7] * acc[7]);
;                 *(u32x4*)(Y + (size_t)row * 1024 + c8) = o;
;             }
	v_lshlrev_b32_e32 v32, 16, v82
	v_and_b32_e32 v33, 0xffff0000, v82
	v_lshlrev_b32_e32 v34, 16, v86
	v_and_b32_e32 v35, 0xffff0000, v86
	v_pk_mul_f32 v[24:25], v[106:107], v[32:33]
	v_pk_mul_f32 v[24:25], v[24:25], v[34:35]
	v_lshlrev_b32_e32 v32, 16, v83
	v_and_b32_e32 v33, 0xffff0000, v83
	v_lshlrev_b32_e32 v34, 16, v87
	v_and_b32_e32 v35, 0xffff0000, v87
	v_pk_mul_f32 v[26:27], v[108:109], v[32:33]
	v_pk_mul_f32 v[26:27], v[26:27], v[34:35]
	v_lshlrev_b32_e32 v32, 16, v84
	v_and_b32_e32 v33, 0xffff0000, v84
	v_lshlrev_b32_e32 v34, 16, v88
	v_and_b32_e32 v35, 0xffff0000, v88
	v_pk_mul_f32 v[28:29], v[110:111], v[32:33]
	v_pk_mul_f32 v[28:29], v[28:29], v[34:35]
	v_lshlrev_b32_e32 v32, 16, v85
	v_and_b32_e32 v33, 0xffff0000, v85
	v_lshlrev_b32_e32 v34, 16, v89
	v_and_b32_e32 v35, 0xffff0000, v89
	v_pk_mul_f32 v[30:31], v[112:113], v[32:33]
	v_pk_mul_f32 v[30:31], v[30:31], v[34:35]
	v_cmp_ne_u32_e32 vcc, 0, v39
	s_and_saveexec_b64 s[6:7], vcc
	v_lshlrev_b32_e32 v32, 16, v90
	v_and_b32_e32 v33, 0xffff0000, v90
	v_lshlrev_b32_e32 v34, 16, v94
	v_and_b32_e32 v35, 0xffff0000, v94
	v_pk_mul_f32 v[36:37], v[114:115], v[32:33]
	v_pk_fma_f32 v[24:25], v[36:37], v[34:35], v[24:25]
	v_lshlrev_b32_e32 v32, 16, v91
	v_and_b32_e32 v33, 0xffff0000, v91
	v_lshlrev_b32_e32 v34, 16, v95
	v_and_b32_e32 v35, 0xffff0000, v95
	v_pk_mul_f32 v[36:37], v[116:117], v[32:33]
	v_pk_fma_f32 v[26:27], v[36:37], v[34:35], v[26:27]
	v_lshlrev_b32_e32 v32, 16, v92
	v_and_b32_e32 v33, 0xffff0000, v92
	v_lshlrev_b32_e32 v34, 16, v96
	v_and_b32_e32 v35, 0xffff0000, v96
	v_pk_mul_f32 v[36:37], v[118:119], v[32:33]
	v_pk_fma_f32 v[28:29], v[36:37], v[34:35], v[28:29]
	v_lshlrev_b32_e32 v32, 16, v93
	v_and_b32_e32 v33, 0xffff0000, v93
	v_lshlrev_b32_e32 v34, 16, v97
	v_and_b32_e32 v35, 0xffff0000, v97
	v_pk_mul_f32 v[36:37], v[120:121], v[32:33]
	v_pk_fma_f32 v[30:31], v[36:37], v[34:35], v[30:31]
	s_or_b64 exec, exec, s[6:7]
	v_cmp_lt_u32_e32 vcc, 1, v39
	s_and_saveexec_b64 s[6:7], vcc
	v_lshlrev_b32_e32 v32, 16, v98
	v_and_b32_e32 v33, 0xffff0000, v98
	v_lshlrev_b32_e32 v34, 16, v102
	v_and_b32_e32 v35, 0xffff0000, v102
	v_pk_mul_f32 v[36:37], v[122:123], v[32:33]
	v_pk_fma_f32 v[24:25], v[36:37], v[34:35], v[24:25]
	v_lshlrev_b32_e32 v32, 16, v99
	v_and_b32_e32 v33, 0xffff0000, v99
	v_lshlrev_b32_e32 v34, 16, v103
	v_and_b32_e32 v35, 0xffff0000, v103
	v_pk_mul_f32 v[36:37], v[124:125], v[32:33]
	v_pk_fma_f32 v[26:27], v[36:37], v[34:35], v[26:27]
	v_lshlrev_b32_e32 v32, 16, v100
	v_and_b32_e32 v33, 0xffff0000, v100
	v_lshlrev_b32_e32 v34, 16, v104
	v_and_b32_e32 v35, 0xffff0000, v104
	v_pk_mul_f32 v[36:37], v[126:127], v[32:33]
	v_pk_fma_f32 v[28:29], v[36:37], v[34:35], v[28:29]
	v_lshlrev_b32_e32 v32, 16, v101
	v_and_b32_e32 v33, 0xffff0000, v101
	v_lshlrev_b32_e32 v34, 16, v105
	v_and_b32_e32 v35, 0xffff0000, v105
	v_pk_mul_f32 v[36:37], v[128:129], v[32:33]
	v_pk_fma_f32 v[30:31], v[36:37], v[34:35], v[30:31]
	s_or_b64 exec, exec, s[6:7]
	v_lshlrev_b32_e32 v32, 16, v78
	v_and_b32_e32 v33, 0xffff0000, v78
	v_pk_mul_f32 v[36:37], v[24:25], v[32:33]
	v_cvt_pk_bf16_f32 v40, v36, v37
	v_lshlrev_b32_e32 v32, 16, v79
	v_and_b32_e32 v33, 0xffff0000, v79
	v_pk_mul_f32 v[36:37], v[26:27], v[32:33]
	v_cvt_pk_bf16_f32 v41, v36, v37
	v_lshlrev_b32_e32 v32, 16, v80
	v_and_b32_e32 v33, 0xffff0000, v80
	v_pk_mul_f32 v[36:37], v[28:29], v[32:33]
	v_cvt_pk_bf16_f32 v42, v36, v37
	v_lshlrev_b32_e32 v32, 16, v81
	v_and_b32_e32 v33, 0xffff0000, v81
	v_pk_mul_f32 v[36:37], v[30:31], v[32:33]
	v_cvt_pk_bf16_f32 v43, v36, v37
	global_store_dwordx4 v[132:133], v[40:43], off
	s_addk_i32 s2, 0x400
	s_cmp_eq_u32 s2, 0
	s_cbranch_scc0 .LBB0_270
